# attention work queue: each workgroup's first item is its block id (no atomic, restores the item->XCD affinity), queue counters start at gridDim.x
# speedup vs baseline: 1.0011x; 1.0011x over previous
; __global__ __launch_bounds__(NTHR, 1) void hymba_mega(Params P) {
;   extern __shared__ __attribute__((aligned(16))) char lds[];
;   cg::grid_group grid = cg::this_grid();
;   unsigned* bctr = reinterpret_cast<unsigned*>(P.ws + O_CONST + 8192 - 256);
;   if (blockIdx.x == 0 && threadIdx.x == 0) *bctr = 0u;
;   if (blockIdx.x == 0 && threadIdx.x < 64) reinterpret_cast<unsigned*>(P.ws + O_CONST + 8192 - 512)[threadIdx.x] = 0u;
.LBB0_2:
	s_or_b64 exec, exec, s[4:5]
	s_load_dwordx16 s[4:19], s[0:1], 0x0
	s_cmp_eq_u32 s98, 0
	v_cmp_gt_u32_e32 vcc, 64, v226
	s_waitcnt lgkmcnt(0)
	v_writelane_b32 v254, s4, 0
	s_nop 1
	v_writelane_b32 v254, s5, 1
	v_writelane_b32 v254, s6, 2
	v_writelane_b32 v254, s7, 3
	v_writelane_b32 v254, s8, 4
	v_writelane_b32 v254, s9, 5
	v_writelane_b32 v254, s10, 6
	v_writelane_b32 v254, s11, 7
	v_writelane_b32 v254, s12, 8
	v_writelane_b32 v254, s13, 9
	v_writelane_b32 v254, s14, 10
	v_writelane_b32 v254, s15, 11
	v_writelane_b32 v254, s16, 12
	v_writelane_b32 v254, s17, 13
	v_writelane_b32 v254, s18, 14
	v_writelane_b32 v254, s19, 15
	s_cselect_b64 s[8:9], -1, 0
	s_and_b64 s[6:7], s[8:9], vcc
	s_and_saveexec_b64 s[4:5], s[6:7]
	s_cbranch_execz .LBB0_4
	v_lshlrev_b32_e32 v2, 2, v226
	v_mov_b32_e32 v3, 0
	v_lshl_add_u64 v[4:5], s[58:59], 0, v[2:3]
	v_add_co_u32_e32 v4, vcc, 0xf7a1000, v4
	s_nop 1
	v_addc_co_u32_e32 v5, vcc, 0, v5, vcc
	v_and_b32_e32 v6, 15, v226
	v_cmp_eq_u32_e32 vcc, 0, v6
	v_mov_b32_e32 v6, s26
	s_nop 0
	v_cndmask_b32_e32 v6, 0, v6, vcc
	global_store_dword v[4:5], v6, off offset:3584

; DEV void grid_bar(unsigned* ctr, unsigned target) {
;   asm volatile("s_waitcnt vmcnt(0)" ::: "memory");
;   __syncthreads();
;   if (threadIdx.x == 0) {
;     __builtin_amdgcn_fence(__ATOMIC_RELEASE, "agent");
;     asm volatile("s_waitcnt vmcnt(0)" ::: "memory");
;     __hip_atomic_fetch_add(ctr, 1u, __ATOMIC_RELAXED, __HIP_MEMORY_SCOPE_AGENT);
;     while (__hip_atomic_load(ctr, __ATOMIC_RELAXED, __HIP_MEMORY_SCOPE_AGENT) < target) __builtin_amdgcn_s_sleep(1);
;     __builtin_amdgcn_fence(__ATOMIC_ACQUIRE, "agent");
;     asm volatile("s_waitcnt vmcnt(0)" ::: "memory");
;   }
;   __syncthreads();
; }
.Lgb_loop_0:
	v_mov_b64_e32 v[0:1], s[4:5]
	flat_load_dword v240, v[0:1] sc1
	flat_load_dword v241, v[0:1] offset:256 sc1
	flat_load_dword v242, v[0:1] offset:512 sc1
	flat_load_dword v243, v[0:1] offset:768 sc1
	s_waitcnt vmcnt(0) lgkmcnt(0)
	v_add3_u32 v240, v240, v241, v242
	v_add_u32_e32 v240, v240, v243
	s_nop 0
	v_readfirstlane_b32 s12, v240
	s_cmp_ge_u32 s12, s10
	s_cbranch_scc1 .Lgb_done_0
	s_sleep 6
	s_add_u32 s11, s11, 1
	s_cmp_lt_u32 s11, 0x20000
	s_cbranch_scc1 .Lgb_loop_0

; DEV void phase_attn(const Params& P, int layer, int batch, char* lds) {
;   unsigned* ctr = reinterpret_cast<unsigned*>(P.ws + O_CONST + 8192 - 512) + (batch * 2 + layer) * 16;
;   volatile int* qw = reinterpret_cast<volatile int*>(lds + LDS_WS + 2048 - 16);
.LBB0_365:
	s_or_b64 exec, exec, s[2:3]
	v_readlane_b32 s4, v254, 18
	v_readlane_b32 s5, v254, 19
	v_readlane_b32 s8, v254, 22
	v_readlane_b32 s9, v254, 23
	v_readlane_b32 s10, v254, 24
	v_readlane_b32 s11, v254, 25
	s_mov_b64 s[4:5], s[10:11]
	s_mov_b64 s[2:3], s[8:9]
	s_barrier
	s_lshl_b32 s2, s51, 4
	v_readlane_b32 s3, v254, 31
	s_or_b32 s22, s2, s3
	s_lshl_b64 s[2:3], s[22:23], 2
	s_add_u32 s2, s4, s2
	v_readlane_b32 s6, v254, 20
	s_addc_u32 s3, s5, s3
	v_readlane_b32 s7, v254, 21
	s_add_u32 s6, s2, 0xf7a1e00
	s_addc_u32 s7, s3, 0
	s_lshl_b32 s22, s51, 10
	s_lshl_b64 s[2:3], s[22:23], 2
	s_add_u32 s2, s4, s2
	s_addc_u32 s3, s5, s3
	s_add_u32 s8, s2, 0xf7a0000
	s_addc_u32 s9, s3, 0
	s_add_u32 s10, s4, 0x4000000
	s_addc_u32 s11, s5, 0
	s_add_u32 s34, s4, 0x5000000
	s_addc_u32 s35, s5, 0
	s_add_u32 s36, s4, 0x6000000
	s_addc_u32 s38, s5, 0
	s_add_u32 s12, s2, 0xf7a0300
	s_addc_u32 s13, s3, 0
	s_add_u32 s14, s4, 0x7000000
	s_addc_u32 s15, s5, 0
	s_add_u32 s16, s4, 0xa000000
	s_addc_u32 s17, s5, 0
	s_add_u32 s48, s4, 0xb800000
	s_addc_u32 s52, s5, 0
	s_add_u32 s53, s4, 0xd000000
	s_addc_u32 s54, s5, 0
	s_add_u32 s55, s4, 0x6010000
	s_addc_u32 s60, s5, 0
	s_add_u32 s61, s4, 0x5010000
	s_addc_u32 s62, s5, 0
	s_mov_b32 s100, 0x5a5a5a5a
	s_branch .LBB0_369

; DEV void attn_a_item(const Params& P, int layer, int batch, int item, char* lds) {
;   const int tid = opaque_tid(), wid = tid >> 6, lane = tid & 63, r32 = lane & 31, hi = lane >> 5;
;   const int seqlen = batch ? 16384 : 4096;
;   const int head = 3 - (item >> 7), k_ = item & 127;
;   const int kk_ = batch ? k_ : (k_ >> 2), mid_ = batch ? 64 : 16;
;   const int qb = mid_ + ((kk_ & 1) ? -((kk_ + 1) >> 1) : (kk_ >> 1));
;   const int seq = batch ? 0 : (k_ & 3);
;   const long tok0 = (long)seq * 4096;
;   const int c = wid >> 2, wq = wid & 3;
;   const int qpos = qb * 128 + wq * 32 + r32;
;   char* V_lds = lds; char* K_lds = lds + 32768;
;   float* wsl = reinterpret_cast<float*>(lds + LDS_WS) + wid * 64;
;   const float lam = WS{P.ws}.consts()[layer * 1024 + 0], nMC = -WS{P.ws}.consts()[layer * 1024 + 1], lam_init = WS{P.ws}.consts()[layer * 1024 + 3];
;   const float nslope = -exp2f(-2.f * (float)(head + 1)) * LOG2E;
;   bf16x8 qr[4];
;   {
;     const u16* Qw = WS{P.ws}.QA() + (tok0 + qpos) * 512 + head * 128 + c * 64 + hi * 8;
; #pragma unroll
;     for (int ks = 0; ks < 4; ++ks) qr[ks] = *reinterpret_cast<const bf16x8*>(Qw + ks * 16);
;   }
;   const u16* Kh = WS{P.ws}.KA() + tok0 * 512 + head * 128;
;   const u16* Vh = WS{P.ws}.VA() + tok0 * 512 + head * 128;
;   int akoff[2], avoff[2], ldst[2];
; #pragma unroll
;   for (int i = 0; i < 2; ++i) {
;     const int p = (wid + 8 * i) * 1024 + lane * 16;
;     ldst[i] = p;
;     const int row = p >> 8, cB = (p & 255) ^ ((row & 7) << 4);
;     akoff[i] = row * 512 + (cB >> 1);
;     const int st = p >> 9, within = p & 511, kk = (st >> 2) * 8 + (within >> 6);
;     const int k = kk, col = (st & 3) * 32 + ((within & 63) >> 1);
;     avoff[i] = k * 512 + col;
;   }
; DEV void phase_attn(const Params& P, int layer, int batch, char* lds) {
;   unsigned* ctr = reinterpret_cast<unsigned*>(P.ws + O_CONST + 8192 - 512) + (batch * 2 + layer) * 16;
;   volatile int* qw = reinterpret_cast<volatile int*>(lds + LDS_WS + 2048 - 16);
;   for (;;) {
;     if (threadIdx.x == 0) *qw = (int)__hip_atomic_fetch_add(ctr, 1u, __ATOMIC_RELAXED, __HIP_MEMORY_SCOPE_AGENT);
;     __syncthreads();
;     const int it = __builtin_amdgcn_readfirstlane(*qw);
;     __syncthreads();
;     if (it >= 768) break;
;     if (it < 256) attn_b_item(P, layer, batch, it, lds);
;     else          attn_a_item(P, layer, batch, it - 256, lds);
.LBB0_369:
	s_and_saveexec_b64 s[2:3], s[0:1]
	s_cbranch_execz .LBB0_371
	s_cmp_eq_u32 s100, 0x5a5a5a5a
	s_cbranch_scc1 .Lq_first
	v_mov_b64_e32 v[0:1], s[6:7]
	flat_atomic_add v2, v[0:1], v228 sc0
	s_branch .Lq_join
.Lq_first:
	v_readlane_b32 s18, v254, 26
	s_nop 3
	v_mov_b32_e32 v2, s18
.Lq_join:
	s_mov_b64 s[18:19], src_shared_base
	s_add_i32 s18, 0, 0x207f0
	s_cmp_lg_u32 s18, -1
	s_cselect_b32 s18, s18, 0
	s_cselect_b32 s19, s19, 0
	v_mov_b32_e32 v0, s18
	v_mov_b32_e32 v1, s19
	s_waitcnt vmcnt(0) lgkmcnt(0)
	flat_store_dword v[0:1], v2 sc0 sc1
	s_waitcnt vmcnt(0)
.LBB0_371:
	s_or_b64 exec, exec, s[2:3]
	s_mov_b32 s100, 0
	s_add_i32 s2, 0, 0x207f0
	s_cmp_lg_u32 s2, -1
	s_cselect_b32 s2, s2, 0
	s_cselect_b32 s3, s21, 0
	v_mov_b32_e32 v0, s2
	v_mov_b32_e32 v1, s3
	s_waitcnt lgkmcnt(0)
	s_barrier
	flat_load_dword v0, v[0:1] sc0 sc1
	s_waitcnt vmcnt(0)
	s_mov_b64 s[2:3], -1
	s_waitcnt lgkmcnt(0)
	s_barrier
	v_readfirstlane_b32 s63, v0
	s_cmpk_gt_i32 s63, 0x2ff
	s_cbranch_scc1 .LBB0_368
	s_cmpk_gt_i32 s63, 0xff
	s_cbranch_scc0 .LBB0_390
	s_add_i32 s22, s63, 0xffffff00
	s_and_b32 s18, s63, 0x7f
	s_bfe_u32 s19, s63, 0x50002
	s_and_b64 s[2:3], s[26:27], exec
	s_cselect_b32 s2, s19, s18
	s_add_i32 s18, s2, 1
	s_lshr_b32 s18, s18, 1
	s_and_b32 s3, s2, 1
	s_sub_i32 s18, 0, s18
	s_lshr_b32 s2, s2, 1
	s_cmp_eq_u32 s3, 0
	s_cselect_b32 s2, s2, s18
	v_readlane_b32 s3, v254, 32
	v_mov_b32_e32 v159, v226
	s_add_i32 s24, s2, s3
	s_lshl_b32 s2, s22, 12
	s_and_b32 s18, s2, 0x3000
	v_ashrrev_i32_e32 v4, 6, v159
	s_and_b64 s[2:3], s[26:27], exec
	v_lshlrev_b32_e32 v161, 5, v4
	v_and_b32_e32 v162, 31, v159
	s_cselect_b32 s19, 0, 0
	s_cselect_b32 s18, s18, 0
	s_lshl_b32 s64, s24, 7
	v_and_b32_e32 v163, 0x60, v161
	v_or3_b32 v0, v162, s64, v163
	s_lshr_b32 s2, s22, 6
	s_and_b32 s2, s2, 6
	v_ashrrev_i32_e32 v1, 31, v0
	s_or_b32 s2, s2, -8
	v_lshl_add_u64 v[0:1], s[18:19], 0, v[0:1]
	v_ashrrev_i32_e32 v164, 8, v159
	v_mov_b64_e32 v[2:3], s[8:9]
	v_ldexp_f32 v13, 1.0, s2
	v_lshlrev_b64 v[0:1], 10, v[0:1]
	s_andn2_b32 s2, 0x180, s22
	flat_load_dwordx2 v[128:129], v[2:3]
	flat_load_dword v158, v[2:3] offset:12
	v_lshl_add_u64 v[0:1], s[10:11], 0, v[0:1]
	s_lshl_b32 s22, s2, 1
	v_lshlrev_b32_e32 v2, 6, v164
	v_and_b32_e32 v165, 63, v159
	v_lshl_add_u64 v[0:1], v[0:1], 0, s[22:23]
	v_ashrrev_i32_e32 v3, 31, v2
	v_lshl_add_u64 v[0:1], v[2:3], 1, v[0:1]
	v_lshlrev_b32_e32 v6, 10, v4
	v_lshlrev_b32_e32 v3, 4, v165
	v_bfe_u32 v8, v159, 2, 3
	v_or_b32_e32 v166, v6, v3
	v_ashrrev_i32_e32 v4, 8, v6
	v_lshlrev_b32_e32 v11, 3, v165
	v_and_or_b32 v9, v4, s45, v8
	v_lshrrev_b32_e32 v5, 4, v166
	v_bfe_u32 v160, v159, 5, 1
	s_lshl_b32 s2, s18, 10
	v_and_b32_e32 v2, 24, v11
	v_and_b32_e32 v5, 0x60, v5
	v_lshlrev_b32_e32 v9, 9, v9
	v_lshlrev_b32_e32 v184, 4, v160
	s_add_u32 s24, s34, s2
	v_or3_b32 v14, v9, v5, v2
	v_add_u32_e32 v9, 0x2000, v6
	v_lshl_add_u64 v[0:1], v[0:1], 0, v[184:185]
	s_addc_u32 s25, s35, 0
	v_or_b32_e32 v15, v9, v3
	v_mul_f32_e32 v130, 0xbfb8aa3b, v13
	flat_load_dwordx4 v[96:99], v[0:1]
	flat_load_dwordx4 v[100:103], v[0:1] offset:32
	flat_load_dwordx4 v[104:107], v[0:1] offset:64
	flat_load_dwordx4 v[108:111], v[0:1] offset:96
	s_add_u32 s65, s36, s2
	v_ashrrev_i32_e32 v0, 8, v166
	v_ashrrev_i32_e32 v6, 8, v15
	v_div_scale_f32 v13, s[2:3], v130, v130, s46
	v_and_b32_e32 v7, 0xf0, v3
	v_lshlrev_b32_e32 v1, 4, v0
	v_lshlrev_b32_e32 v10, 4, v6
	v_rcp_f32_e32 v19, v13
	v_bitop3_b32 v1, v1, v7, s95 bitop3:0x6c
	v_bitop3_b32 v7, v10, v7, s95 bitop3:0x6c
	v_ashrrev_i32_e32 v10, 8, v9
	v_and_or_b32 v17, v10, s45, v8
	v_lshrrev_b32_e32 v15, 4, v15
	v_and_b32_e32 v15, 0x60, v15
	v_lshlrev_b32_e32 v17, 9, v17
	v_or3_b32 v18, v17, v15, v2
	v_fma_f32 v15, -v13, v19, 1.0
	v_fmac_f32_e32 v19, v15, v19
	v_div_scale_f32 v15, vcc, s46, v130, s46
	v_mul_f32_e32 v17, v15, v19
	v_fma_f32 v20, -v13, v17, v15
	v_fmac_f32_e32 v17, v20, v19
	v_fma_f32 v13, -v13, v17, v15
	v_div_fmas_f32 v13, v13, v19, v17
	v_div_fixup_f32 v13, v13, v130, s46
	v_min_f32_e32 v13, 0x49742400, v13
	v_cvt_i32_f32_e32 v13, v13
	s_addc_u32 s68, s38, 0
	s_add_u32 s3, s24, s22
	s_addc_u32 s71, s25, 0
	s_add_u32 s74, s65, s22
	v_readfirstlane_b32 s24, v13
	s_addc_u32 s75, s68, 0
	s_sub_i32 s2, s64, s24
	s_ashr_i32 s2, s2, 6
	s_or_b32 s65, s64, 0x7f
	s_max_i32 s2, s2, 0
	s_add_i32 s24, s65, s24
	s_ashr_i32 s78, s24, 6
	s_lshl_b32 s24, s2, 6
	s_mov_b32 s25, s23
	s_lshl_b64 s[68:69], s[24:25], 10
	v_lshlrev_b32_e32 v0, 9, v0
	v_lshrrev_b32_e32 v1, 1, v1
	s_add_u32 s70, s3, s68
	v_add_u32_e32 v20, 0, v166
	v_or_b32_e32 v12, v1, v0
	s_addc_u32 s71, s71, s69
	v_add_u32_e32 v15, 0x8000, v20
	s_add_u32 s68, s74, s68
	v_ashrrev_i32_e32 v13, 31, v12
	v_readfirstlane_b32 s3, v15
	v_lshlrev_b32_e32 v6, 9, v6
	v_lshrrev_b32_e32 v7, 1, v7
	s_addc_u32 s69, s75, s69
	v_lshl_add_u64 v[12:13], v[12:13], 1, s[70:71]
	s_mov_b32 m0, s3
	v_ashrrev_i32_e32 v15, 31, v14
	v_or_b32_e32 v16, v7, v6
	global_load_lds_dwordx4 v[12:13], off
	v_lshl_add_u64 v[12:13], v[14:15], 1, s[68:69]
	v_readfirstlane_b32 s3, v20
	v_add_u32_e32 v14, 0xa000, v20
	s_mov_b32 m0, s3
	v_ashrrev_i32_e32 v17, 31, v16
	v_readfirstlane_b32 s3, v14
	v_add_u32_e32 v14, 0x2000, v20
	global_load_lds_dwordx4 v[12:13], off
	v_lshl_add_u64 v[12:13], v[16:17], 1, s[70:71]
	s_mov_b32 m0, s3
	v_ashrrev_i32_e32 v19, 31, v18
	v_readfirstlane_b32 s3, v14
	global_load_lds_dwordx4 v[12:13], off
	v_lshl_add_u64 v[12:13], v[18:19], 1, s[68:69]
	s_mov_b32 m0, s3
	s_min_i32 s70, s49, s78
	global_load_lds_dwordx4 v[12:13], off
	s_waitcnt vmcnt(0)
	s_mov_b32 s25, 0
	s_cmp_gt_i32 s2, s70
	s_waitcnt vmcnt(0) lgkmcnt(0)
	s_barrier
	s_cbranch_scc1 .LBB0_382
; DEV int v_rd_base(int lane) { return ((lane & 3) << 3) | (((lane >> 2) & 3) << 6) | (((lane >> 4) & 1) << 5) | (((lane >> 5) & 1) << 8); }
; DEV void attn_a_item(const Params& P, int layer, int batch, int item, char* lds) {
;     ...
;   int akoff[2], avoff[2], ldst[2];
; #pragma unroll
;   for (int i = 0; i < 2; ++i) {
;     const int p = (wid + 8 * i) * 1024 + lane * 16;
;     ldst[i] = p;
;     const int row = p >> 8, cB = (p & 255) ^ ((row & 7) << 4);
;     akoff[i] = row * 512 + (cB >> 1);
;     const int st = p >> 9, within = p & 511, kk = (st >> 2) * 8 + (within >> 6);
;     const int k = kk, col = (st & 3) * 32 + ((within & 63) >> 1);
;     avoff[i] = k * 512 + col;
;   }
;   const int vb0 = (int)(uintptr_t)V_lds + v_rd_base(lane);
;     ...
;   f32x16 o[4] = {f32x16{}, f32x16{}, f32x16{}, f32x16{}};
;   float lsum = 0.f;
;   const int NT = seqlen >> 6;
;   const int Dk = (int)fminf(160.f / -nslope, 1.0e6f);
;     ...
;     for (int ks = 0; ks < 4; ++ks) {
;       const int cb = c * 128 + (ks * 16 + hi * 8) * 2;
;       kf[2 * ks] = *reinterpret_cast<const bf16x8*>(Ks + KSWZ(r32, cb));
;       kf[2 * ks + 1] = *reinterpret_cast<const bf16x8*>(Ks + KSWZ(32 + r32, cb));
;     }
	s_cmp_lg_u32 0, -1
	v_and_b32_e32 v13, 0xc0, v3
	s_cselect_b32 s3, 0, 0
	v_lshlrev_b32_e32 v12, 1, v165
	v_add_u32_e32 v13, s3, v13
	s_mov_b32 s3, s23
	v_and_b32_e32 v12, 32, v12
	v_and_b32_e32 v11, 0x118, v11
	s_lshl_b64 s[68:69], s[2:3], 16
	s_lshl_b64 s[74:75], s[18:19], 10
	v_add_u32_e32 v3, v9, v3
	v_add3_u32 v173, v13, v12, v11
	s_add_u32 s3, s68, s74
	v_lshlrev_b32_e32 v10, 9, v10
	v_lshlrev_b32_e32 v11, 9, v8
	s_movk_i32 s74, 0xf000
	v_lshrrev_b32_e32 v3, 4, v3
	v_and_or_b32 v8, v10, s74, v11
	v_and_b32_e32 v3, 0x60, v3
	v_or3_b32 v8, v8, v3, v2
	v_lshlrev_b32_e32 v3, 9, v4
	s_addc_u32 s71, s69, s75
	v_and_or_b32 v3, v3, s74, v11
	s_add_u32 s68, s55, s3
	v_or3_b32 v2, v3, v5, v2
	v_ashrrev_i32_e32 v9, 31, v8
	s_addc_u32 s69, s60, s71
	v_ashrrev_i32_e32 v3, 31, v2
	v_lshl_add_u64 v[150:151], v[8:9], 1, s[68:69]
	v_lshl_add_u64 v[152:153], v[2:3], 1, s[68:69]
	s_add_u32 s68, s61, s3
	v_add_u32_e32 v0, v1, v0
	v_lshlrev_b32_e32 v14, 2, v160
	s_addc_u32 s69, s62, s71
	v_ashrrev_i32_e32 v1, 31, v0
	v_lshlrev_b32_e32 v15, 7, v164
	v_lshlrev_b32_e32 v17, 4, v159
	v_add_u32_e32 v2, v7, v6
	v_lshl_add_u64 v[156:157], v[0:1], 1, s[68:69]
	v_sub_u32_e32 v0, v14, v162
	v_or_b32_e32 v16, v184, v15
	v_and_b32_e32 v17, 0x70, v17
	v_xor_b32_e32 v132, 0x80000000, v129
	v_ashrrev_i32_e32 v3, 31, v2
	v_sub_u32_e32 v0, v0, v163
	v_mov_b32_e32 v167, 0
	v_lshl_add_u32 v168, v162, 8, 0
	v_bitop3_b32 v169, v184, v17, v15 bitop3:0x36
	v_bitop3_b32 v170, v16, v17, 32 bitop3:0x36
	v_bitop3_b32 v171, v16, v17, 64 bitop3:0x36
	v_bitop3_b32 v172, v16, v17, s56 bitop3:0x36
	v_mov_b32_e32 v134, v130
	v_mov_b32_e32 v135, v130
	v_mov_b32_e32 v133, v132
	v_mov_b32_e32 v136, v132
	v_mov_b32_e32 v137, v132
	v_mov_b32_e32 v138, v132
	v_mov_b32_e32 v139, v132
	v_mov_b32_e32 v140, v132
	v_mov_b32_e32 v141, v132
	v_mov_b32_e32 v142, v132
	v_mov_b32_e32 v143, v132
	v_mov_b32_e32 v144, v132
	v_mov_b32_e32 v145, v132
	v_mov_b32_e32 v146, v132
	v_mov_b32_e32 v147, v132
	v_mov_b32_e32 v148, v132
	v_mov_b32_e32 v149, v132
	v_lshl_add_u64 v[154:155], v[2:3], 1, s[68:69]
	v_subrev_u32_e32 v174, s64, v0
	v_mov_b32_e32 v48, 0
	v_mov_b32_e32 v49, v167
	v_mov_b32_e32 v50, v167
	v_mov_b32_e32 v51, v167
	v_mov_b32_e32 v52, v167
	v_mov_b32_e32 v53, v167
	v_mov_b32_e32 v54, v167
	v_mov_b32_e32 v55, v167
	v_mov_b32_e32 v56, v167
	v_mov_b32_e32 v57, v167
	v_mov_b32_e32 v58, v167
	v_mov_b32_e32 v59, v167
	v_mov_b32_e32 v60, v167
	v_mov_b32_e32 v61, v167
	v_mov_b32_e32 v62, v167
	v_mov_b32_e32 v63, v167
	v_mov_b32_e32 v32, 0
	v_mov_b32_e32 v33, v167
	v_mov_b32_e32 v34, v167
	v_mov_b32_e32 v35, v167
	v_mov_b32_e32 v36, v167
	v_mov_b32_e32 v37, v167
	v_mov_b32_e32 v38, v167
	v_mov_b32_e32 v39, v167
	v_mov_b32_e32 v40, v167
	v_mov_b32_e32 v41, v167
	v_mov_b32_e32 v42, v167
	v_mov_b32_e32 v43, v167
	v_mov_b32_e32 v44, v167
	v_mov_b32_e32 v45, v167
	v_mov_b32_e32 v46, v167
	v_mov_b32_e32 v47, v167
	v_mov_b32_e32 v16, 0
	v_mov_b32_e32 v17, v167
	v_mov_b32_e32 v18, v167
	v_mov_b32_e32 v19, v167
	v_mov_b32_e32 v20, v167
	v_mov_b32_e32 v21, v167
	v_mov_b32_e32 v22, v167
	v_mov_b32_e32 v23, v167
	v_mov_b32_e32 v24, v167
	v_mov_b32_e32 v25, v167
	v_mov_b32_e32 v26, v167
	v_mov_b32_e32 v27, v167
	v_mov_b32_e32 v28, v167
	v_mov_b32_e32 v29, v167
	v_mov_b32_e32 v30, v167
	v_mov_b32_e32 v31, v167
	v_mov_b32_e32 v0, 0
	v_mov_b32_e32 v1, v167
	v_mov_b32_e32 v2, v167
	v_mov_b32_e32 v3, v167
	v_mov_b32_e32 v4, v167
	v_mov_b32_e32 v5, v167
	v_mov_b32_e32 v6, v167
	v_mov_b32_e32 v7, v167
	v_mov_b32_e32 v8, v167
	v_mov_b32_e32 v9, v167
	v_mov_b32_e32 v10, v167
	v_mov_b32_e32 v11, v167
	v_mov_b32_e32 v12, v167
	v_mov_b32_e32 v13, v167
	v_mov_b32_e32 v14, v167
	v_mov_b32_e32 v15, v167
	v_add_u32_e32 v186, v168, v169
	v_add_u32_e32 v187, v168, v170
	v_add_u32_e32 v188, v168, v171
	v_add_u32_e32 v189, v168, v172
	v_add_u32_e32 v186, 0x8000, v186
	v_add_u32_e32 v187, 0x8000, v187
	v_add_u32_e32 v188, 0x8000, v188
	v_add_u32_e32 v189, 0x8000, v189
	v_and_b32_e32 v218, 3, v162
	v_lshlrev_b32_e32 v218, 2, v218
	v_bfe_u32 v219, v162, 2, 2
	v_or_b32_e32 v218, v218, v219
	v_lshl_or_b32 v219, v164, 3, v160
	v_or_b32_e32 v220, 0, v219
	v_xor_b32_e32 v220, v220, v218
	v_lshl_add_u32 v169, v220, 4, v168
	v_add_u32_e32 v169, 0x8000, v169
; DEV int v_rd_base(int lane) { return ((lane & 3) << 3) | (((lane >> 2) & 3) << 6) | (((lane >> 4) & 1) << 5) | (((lane >> 5) & 1) << 8); }
; DEV void attn_a_item(const Params& P, int layer, int batch, int item, char* lds) {
;     ...
;   int akoff[2], avoff[2], ldst[2];
; #pragma unroll
;   for (int i = 0; i < 2; ++i) {
;     const int p = (wid + 8 * i) * 1024 + lane * 16;
;     ldst[i] = p;
;     const int row = p >> 8, cB = (p & 255) ^ ((row & 7) << 4);
;     akoff[i] = row * 512 + (cB >> 1);
;     const int st = p >> 9, within = p & 511, kk = (st >> 2) * 8 + (within >> 6);
;     const int k = kk, col = (st & 3) * 32 + ((within & 63) >> 1);
;     avoff[i] = k * 512 + col;
;   }
;   const int vb0 = (int)(uintptr_t)V_lds + v_rd_base(lane);
;     ...
;     const char* Ks = K_lds + bcur * 16384;
;     f32x16 p0, p1;
;     {
;       const float dbase = (float)(j * 64 - qpos + 4 * hi);
;       const int q0 = qb * 128;
;       if (j * 64 + 63 < q0 || j * 64 > q0 + 127) {
;         const float step = (j * 64 < q0) ? -nslope : nslope;
;         const float base = fmaf(dbase, step, nMC), step8 = 8.f * step;
;         p0[0] = base; p0[1] = base + step; p0[2] = fmaf(2.f, step, base); p0[3] = fmaf(3.f, step, base);
; #pragma unroll
;         for (int r = 4; r < 16; ++r) p0[r] = p0[r - 4] + step8;
; #pragma unroll
;         for (int r = 0; r < 4; ++r) p1[r] = p0[r + 12] + step8;
; #pragma unroll
;         for (int r = 4; r < 16; ++r) p1[r] = p1[r - 4] + step8;
;       } else {
;         float d0[16], d1[16];
;         d0[0] = dbase; d0[1] = dbase + 1.f; d0[2] = dbase + 2.f; d0[3] = d0[1] + 2.f;
; #pragma unroll
;         for (int r = 4; r < 16; ++r) d0[r] = d0[r - 4] + 8.f;
; #pragma unroll
;         for (int r = 0; r < 4; ++r) d1[r] = d0[r + 12] + 8.f;
; #pragma unroll
;         for (int r = 4; r < 16; ++r) d1[r] = d1[r - 4] + 8.f;
; #pragma unroll
;         for (int r = 0; r < 16; ++r) { p0[r] = fmaf(fabsf(d0[r]), nslope, nMC); p1[r] = fmaf(fabsf(d1[r]), nslope, nMC); }
;       }
;     }
;     const int vb = vb0 + bcur * 16384;
;     bf16x8 pa0, pa1, pa2, pa3;
;     s16x4 fa[8], fb[8];
;     bf16x8 kf[8];
; #pragma unroll
;     for (int ks = 0; ks < 4; ++ks) {
;       const int cb = c * 128 + (ks * 16 + hi * 8) * 2;
;       kf[2 * ks] = *reinterpret_cast<const bf16x8*>(Ks + KSWZ(r32, cb));
;       kf[2 * ks + 1] = *reinterpret_cast<const bf16x8*>(Ks + KSWZ(32 + r32, cb));
;     }
	v_or_b32_e32 v220, 2, v219
	v_xor_b32_e32 v220, v220, v218
	v_lshl_add_u32 v170, v220, 4, v168
	v_add_u32_e32 v170, 0x8000, v170
	v_or_b32_e32 v220, 4, v219
	v_xor_b32_e32 v220, v220, v218
	v_lshl_add_u32 v171, v220, 4, v168
	v_add_u32_e32 v171, 0x8000, v171
	v_or_b32_e32 v220, 6, v219
	v_xor_b32_e32 v220, v220, v218
	v_lshl_add_u32 v172, v220, 4, v168
	v_add_u32_e32 v172, 0x8000, v172
	v_readfirstlane_b32 s100, v166
	v_readfirstlane_b32 s25, v130
	v_cvt_f32_i32_e32 v166, v174
	s_nop 0
	v_mov_b32_e32 v112, v166
	v_add_f32_e32 v113, 0x3f800000, v166
	v_add_f32_e32 v114, 0x40000000, v166
	v_add_f32_e32 v115, 0x40400000, v166
	v_add_f32_e32 v116, 0x41000000, v166
	v_add_f32_e32 v117, 0x41100000, v166
	v_add_f32_e32 v118, 0x41200000, v166
	v_add_f32_e32 v119, 0x41300000, v166
	v_add_f32_e32 v120, 0x41800000, v166
	v_add_f32_e32 v121, 0x41880000, v166
	v_add_f32_e32 v122, 0x41900000, v166
	v_add_f32_e32 v123, 0x41980000, v166
	v_add_f32_e32 v124, 0x41c00000, v166
	v_add_f32_e32 v125, 0x41c80000, v166
	v_add_f32_e32 v126, 0x41d00000, v166
	v_add_f32_e32 v127, 0x41d80000, v166
	v_add_f32_e32 v133, 0x42000000, v166
	v_add_f32_e32 v134, 0x42040000, v166
	v_add_f32_e32 v135, 0x42080000, v166
	v_add_f32_e32 v136, 0x420c0000, v166
	v_add_f32_e32 v137, 0x42200000, v166
	v_add_f32_e32 v138, 0x42240000, v166
	v_add_f32_e32 v139, 0x42280000, v166
	v_add_f32_e32 v140, 0x422c0000, v166
	v_add_f32_e32 v141, 0x42400000, v166
	v_add_f32_e32 v142, 0x42440000, v166
	v_add_f32_e32 v143, 0x42480000, v166
	v_add_f32_e32 v144, 0x424c0000, v166
	v_add_f32_e32 v145, 0x42600000, v166
	v_add_f32_e32 v146, 0x42640000, v166
	v_add_f32_e32 v147, 0x42680000, v166
	v_add_f32_e32 v148, 0x426c0000, v166
	v_readfirstlane_b32 s71, v156
	v_readfirstlane_b32 s101, v157
	s_nop 3
	s_sub_u32 s71, s71, 0x1000
	s_subb_u32 s101, s101, 0
	v_subrev_u32_e32 v174, s71, v156
	v_subrev_u32_e32 v175, s71, v154
	s_add_u32 s68, s71, s22
	s_addc_u32 s69, s101, 0
	v_lshrrev_b32_e32 v221, 6, v159
	v_bfe_u32 v222, v165, 4, 2
	v_lshlrev_b32_e32 v222, 2, v222
	v_and_b32_e32 v223, 3, v221
	v_or_b32_e32 v222, v222, v223
	v_and_b32_e32 v223, 15, v165
	v_xor_b32_e32 v223, v223, v222
	v_lshrrev_b32_e32 v224, 4, v165
	v_lshlrev_b32_e32 v224, 10, v224
	v_lshl_add_u32 v224, v223, 4, v224
	v_and_b32_e32 v225, 1, v221
	v_lshlrev_b32_e32 v225, 6, v225
	v_sub_u32_e32 v224, v224, v225
	v_add_u32_e32 v174, 0x1000, v224
	v_add_u32_e32 v175, 0x8000, v174
	v_readfirstlane_b32 s71, v152
	v_readfirstlane_b32 s101, v153
	s_nop 3
	s_sub_u32 s71, s71, 0x1000
	s_subb_u32 s101, s101, 0
	v_subrev_u32_e32 v149, s71, v152
	v_subrev_u32_e32 v131, s71, v150
	s_add_u32 s74, s71, s22
	s_addc_u32 s75, s101, 0
	s_xor_b32 s65, s25, 0x80000000
	s_lshr_b32 s78, s64, 6
	v_mov_b32_e32 v154, 0
	v_mov_b32_e32 v155, 0
	v_mov_b32_e32 v156, 0
	v_mov_b32_e32 v157, 0
	v_mov_b32_e32 v202, 0
	v_mov_b32_e32 v203, 0
	v_mov_b32_e32 v204, 0
	v_mov_b32_e32 v205, 0
	v_mov_b32_e32 v206, 0
	v_mov_b32_e32 v207, 0
	v_mov_b32_e32 v208, 0
	v_mov_b32_e32 v209, 0
	v_mov_b32_e32 v210, 0
	v_mov_b32_e32 v211, 0
	v_mov_b32_e32 v212, 0
	v_mov_b32_e32 v213, 0
	v_mov_b32_e32 v214, 0
	v_mov_b32_e32 v215, 0
	v_mov_b32_e32 v216, 0
	v_mov_b32_e32 v217, 0
	s_cmp_lt_i32 s2, s78
	s_cselect_b32 s3, s65, s25
	s_sub_u32 s71, s2, s78
	s_cmp_lt_u32 s71, 2
	s_cselect_b64 vcc, -1, 0
	v_cvt_f32_i32_e32 v129, s24
	s_nop 0
	v_fma_f32 v168, v129, s3, v132
	ds_read_b128 v[218:221], v186 offset:0
	ds_read_b128 v[222:225], v187 offset:0
	ds_read_b128 v[232:235], v188 offset:0
	ds_read_b128 v[236:239], v189 offset:0
	ds_read_b128 v[240:243], v186 offset:8192
	ds_read_b128 v[244:247], v187 offset:8192
	ds_read_b128 v[248:251], v188 offset:8192
	ds_read_b128 v[194:197], v189 offset:8192
	s_cbranch_vccnz .Ldfa_diag_f_a
	v_fma_f32 v64, v112, s3, v168
	v_fma_f32 v65, v113, s3, v168
	v_fma_f32 v66, v114, s3, v168
	v_fma_f32 v67, v115, s3, v168
	v_fma_f32 v68, v116, s3, v168
	v_fma_f32 v69, v117, s3, v168
	v_fma_f32 v70, v118, s3, v168
	v_fma_f32 v71, v119, s3, v168
	v_fma_f32 v72, v120, s3, v168
	v_fma_f32 v73, v121, s3, v168
	v_fma_f32 v74, v122, s3, v168
	v_fma_f32 v75, v123, s3, v168
	v_fma_f32 v76, v124, s3, v168
	v_fma_f32 v77, v125, s3, v168
	v_fma_f32 v78, v126, s3, v168
	v_fma_f32 v79, v127, s3, v168
